# drain epilogues (out-proj residual hin f32, GLU gate/source bf16): once-read operands loaded non-temporally
# baseline (speedup 1.0000x reference)
.LBB0_411:
	s_lshl_b32 s28, s10, 17
	v_lshl_add_u64 v[98:99], v[96:97], 0, s[28:29]
	s_lshl_b32 s28, s10, 6
	s_add_i32 s28, s28, s31
	v_cndmask_b32_e64 v64, 0, 1, s[22:23]
	s_mul_i32 s12, s28, 0x410
	s_and_b64 vcc, exec, s[80:81]
	v_cmp_ne_u32_e64 s[6:7], 1, v64
	s_mov_b64 s[8:9], -1
	s_cbranch_vccz .LBB0_461
	v_lshlrev_b64 v[64:65], 1, v[98:99]
	v_lshl_add_u64 v[68:69], s[20:21], 0, v[64:65]
	global_load_dwordx2 v[102:103], v[68:69], off nt
	v_lshl_add_u64 v[64:65], s[34:35], 0, v[64:65]
	v_mov_b32_e32 v100, 0
	s_and_b64 vcc, exec, s[6:7]
	v_mov_b32_e32 v104, 0
	v_mov_b32_e32 v105, 0
	s_cbranch_vccnz .LBB0_414
	global_load_dwordx2 v[104:105], v[64:65], off nt
.LBB0_414:
	v_add_co_u32_e32 v66, vcc, 0x8000, v68
	v_mov_b32_e32 v101, 0
	s_nop 0
	v_addc_co_u32_e32 v67, vcc, 0, v69, vcc
	global_load_dwordx2 v[94:95], v[66:67], off nt
	s_and_b64 vcc, exec, s[6:7]
	s_cbranch_vccnz .LBB0_416
	v_add_co_u32_e32 v66, vcc, 0x8000, v64
	s_nop 1
	v_addc_co_u32_e32 v67, vcc, 0, v65, vcc
	global_load_dwordx2 v[100:101], v[66:67], off nt
.LBB0_416:
	v_add_co_u32_e32 v66, vcc, 0x10000, v68
	v_mov_b32_e32 v88, 0
	s_nop 0
	v_addc_co_u32_e32 v67, vcc, 0, v69, vcc
	global_load_dwordx2 v[90:91], v[66:67], off nt
	s_and_b64 vcc, exec, s[6:7]
	v_mov_b32_e32 v92, 0
	v_mov_b32_e32 v93, 0
	s_cbranch_vccnz .LBB0_418
	v_add_co_u32_e32 v66, vcc, 0x10000, v64
	s_nop 1
	v_addc_co_u32_e32 v67, vcc, 0, v65, vcc
	global_load_dwordx2 v[92:93], v[66:67], off nt
.LBB0_418:
	v_add_co_u32_e32 v66, vcc, 0x18000, v68
	v_mov_b32_e32 v89, 0
	s_nop 0
	v_addc_co_u32_e32 v67, vcc, 0, v69, vcc
	global_load_dwordx2 v[86:87], v[66:67], off nt
	s_and_b64 vcc, exec, s[6:7]
	s_cbranch_vccnz .LBB0_420
	v_add_co_u32_e32 v66, vcc, 0x18000, v64
	s_nop 1
	v_addc_co_u32_e32 v67, vcc, 0, v65, vcc
	global_load_dwordx2 v[88:89], v[66:67], off nt
.LBB0_420:
	v_add_co_u32_e32 v66, vcc, 0x20000, v68
	v_mov_b32_e32 v80, 0
	s_nop 0
	v_addc_co_u32_e32 v67, vcc, 0, v69, vcc
	global_load_dwordx2 v[82:83], v[66:67], off nt
	s_and_b64 vcc, exec, s[6:7]
	v_mov_b32_e32 v84, 0
	v_mov_b32_e32 v85, 0
	s_cbranch_vccnz .LBB0_422
	v_add_co_u32_e32 v66, vcc, 0x20000, v64
	s_nop 1
	v_addc_co_u32_e32 v67, vcc, 0, v65, vcc
	global_load_dwordx2 v[84:85], v[66:67], off nt
.LBB0_422:
	v_add_co_u32_e32 v66, vcc, 0x28000, v68
	v_mov_b32_e32 v81, 0
	s_nop 0
	v_addc_co_u32_e32 v67, vcc, 0, v69, vcc
	global_load_dwordx2 v[78:79], v[66:67], off nt
	s_and_b64 vcc, exec, s[6:7]
	s_cbranch_vccnz .LBB0_424
	v_add_co_u32_e32 v66, vcc, 0x28000, v64
	s_nop 1
	v_addc_co_u32_e32 v67, vcc, 0, v65, vcc
	global_load_dwordx2 v[80:81], v[66:67], off nt
.LBB0_424:
	v_add_co_u32_e32 v66, vcc, 0x30000, v68
	v_mov_b32_e32 v72, 0
	s_nop 0
	v_addc_co_u32_e32 v67, vcc, 0, v69, vcc
	global_load_dwordx2 v[74:75], v[66:67], off nt
	s_and_b64 vcc, exec, s[6:7]
	v_mov_b32_e32 v76, 0
	v_mov_b32_e32 v77, 0
	s_cbranch_vccnz .LBB0_426
	v_add_co_u32_e32 v66, vcc, 0x30000, v64
	s_nop 1
	v_addc_co_u32_e32 v67, vcc, 0, v65, vcc
	global_load_dwordx2 v[76:77], v[66:67], off nt
.LBB0_426:
	v_add_co_u32_e32 v66, vcc, 0x38000, v68
	v_mov_b32_e32 v73, 0
	s_nop 0
	v_addc_co_u32_e32 v67, vcc, 0, v69, vcc
	global_load_dwordx2 v[70:71], v[66:67], off nt
	s_and_b64 vcc, exec, s[6:7]
	s_cbranch_vccnz .LBB0_428
	v_add_co_u32_e32 v64, vcc, 0x38000, v64
	s_nop 1
	v_addc_co_u32_e32 v65, vcc, 0, v65, vcc
	global_load_dwordx2 v[72:73], v[64:65], off nt

.LBB0_528:
	s_lshl_b32 s28, s10, 17
	v_lshl_add_u64 v[34:35], v[32:33], 0, s[28:29]
	s_lshl_b32 s28, s10, 6
	s_add_i32 s42, s28, s31
	s_mulk_i32 s42, 0x410
	s_and_b64 vcc, exec, s[80:81]
	s_mov_b64 s[10:11], -1
	s_cbranch_vccz .LBB0_578
	v_lshlrev_b64 v[0:1], 1, v[34:35]
	v_lshl_add_u64 v[4:5], s[20:21], 0, v[0:1]
	global_load_dwordx2 v[38:39], v[4:5], off nt
	v_lshl_add_u64 v[0:1], s[34:35], 0, v[0:1]
	v_mov_b32_e32 v36, 0
	s_and_b64 vcc, exec, s[6:7]
	v_mov_b32_e32 v40, 0
	v_mov_b32_e32 v41, 0
	s_cbranch_vccnz .LBB0_531
	global_load_dwordx2 v[40:41], v[0:1], off nt
.LBB0_531:
	v_add_co_u32_e32 v2, vcc, 0x8000, v4
	v_mov_b32_e32 v37, 0
	s_nop 0
	v_addc_co_u32_e32 v3, vcc, 0, v5, vcc
	global_load_dwordx2 v[30:31], v[2:3], off nt
	s_and_b64 vcc, exec, s[6:7]
	s_cbranch_vccnz .LBB0_533
	v_add_co_u32_e32 v2, vcc, 0x8000, v0
	s_nop 1
	v_addc_co_u32_e32 v3, vcc, 0, v1, vcc
	global_load_dwordx2 v[36:37], v[2:3], off nt
.LBB0_533:
	v_add_co_u32_e32 v2, vcc, 0x10000, v4
	v_mov_b32_e32 v24, 0
	s_nop 0
	v_addc_co_u32_e32 v3, vcc, 0, v5, vcc
	global_load_dwordx2 v[26:27], v[2:3], off nt
	s_and_b64 vcc, exec, s[6:7]
	v_mov_b32_e32 v28, 0
	v_mov_b32_e32 v29, 0
	s_cbranch_vccnz .LBB0_535
	v_add_co_u32_e32 v2, vcc, 0x10000, v0
	s_nop 1
	v_addc_co_u32_e32 v3, vcc, 0, v1, vcc
	global_load_dwordx2 v[28:29], v[2:3], off nt
.LBB0_535:
	v_add_co_u32_e32 v2, vcc, 0x18000, v4
	v_mov_b32_e32 v25, 0
	s_nop 0
	v_addc_co_u32_e32 v3, vcc, 0, v5, vcc
	global_load_dwordx2 v[22:23], v[2:3], off nt
	s_and_b64 vcc, exec, s[6:7]
	s_cbranch_vccnz .LBB0_537
	v_add_co_u32_e32 v2, vcc, 0x18000, v0
	s_nop 1
	v_addc_co_u32_e32 v3, vcc, 0, v1, vcc
	global_load_dwordx2 v[24:25], v[2:3], off nt
.LBB0_537:
	v_add_co_u32_e32 v2, vcc, 0x20000, v4
	v_mov_b32_e32 v16, 0
	s_nop 0
	v_addc_co_u32_e32 v3, vcc, 0, v5, vcc
	global_load_dwordx2 v[18:19], v[2:3], off nt
	s_and_b64 vcc, exec, s[6:7]
	v_mov_b32_e32 v20, 0
	v_mov_b32_e32 v21, 0
	s_cbranch_vccnz .LBB0_539
	v_add_co_u32_e32 v2, vcc, 0x20000, v0
	s_nop 1
	v_addc_co_u32_e32 v3, vcc, 0, v1, vcc
	global_load_dwordx2 v[20:21], v[2:3], off nt
.LBB0_539:
	v_add_co_u32_e32 v2, vcc, 0x28000, v4
	v_mov_b32_e32 v17, 0
	s_nop 0
	v_addc_co_u32_e32 v3, vcc, 0, v5, vcc
	global_load_dwordx2 v[14:15], v[2:3], off nt
	s_and_b64 vcc, exec, s[6:7]
	s_cbranch_vccnz .LBB0_541
	v_add_co_u32_e32 v2, vcc, 0x28000, v0
	s_nop 1
	v_addc_co_u32_e32 v3, vcc, 0, v1, vcc
	global_load_dwordx2 v[16:17], v[2:3], off nt
.LBB0_541:
	v_add_co_u32_e32 v2, vcc, 0x30000, v4
	v_mov_b32_e32 v8, 0
	s_nop 0
	v_addc_co_u32_e32 v3, vcc, 0, v5, vcc
	global_load_dwordx2 v[10:11], v[2:3], off nt
	s_and_b64 vcc, exec, s[6:7]
	v_mov_b32_e32 v12, 0
	v_mov_b32_e32 v13, 0
	s_cbranch_vccnz .LBB0_543
	v_add_co_u32_e32 v2, vcc, 0x30000, v0
	s_nop 1
	v_addc_co_u32_e32 v3, vcc, 0, v1, vcc
	global_load_dwordx2 v[12:13], v[2:3], off nt
.LBB0_543:
	v_add_co_u32_e32 v2, vcc, 0x38000, v4
	v_mov_b32_e32 v9, 0
	s_nop 0
	v_addc_co_u32_e32 v3, vcc, 0, v5, vcc
	global_load_dwordx2 v[6:7], v[2:3], off nt
	s_and_b64 vcc, exec, s[6:7]
	s_cbranch_vccnz .LBB0_545
	v_add_co_u32_e32 v0, vcc, 0x38000, v0
	s_nop 1
	v_addc_co_u32_e32 v1, vcc, 0, v1, vcc
	global_load_dwordx2 v[8:9], v[0:1], off nt
